# diff attention: two-barrier half-tile stagger of waves 4-7 vs 0-3, K/V ring deepened to 4 slots
# speedup vs baseline: 1.0086x; 1.0019x over previous
; template <int DV, bool BAND> ...
;     ...
;     if (wid >= 4) __builtin_amdgcn_s_setprio(1);
;     int s_cur = 0, s_n2 = 2 * SLOT;
;     for (int t = t0; t < t1; ++t) {
;         asm volatile("s_waitcnt vmcnt(%0)" :: "n"(NP) : "memory");
;         asm volatile("s_waitcnt lgkmcnt(0)\n\ts_barrier" ::: "memory");
.LBB0_768:
	v_readlane_b32 s4, v254, 33
	v_readlane_b32 s5, v254, 34
	s_andn2_b64 vcc, exec, s[4:5]
	s_nop 0
	v_cndmask_b32_e64 v3, 0, 1, s[4:5]
	v_cmp_ne_u32_e64 s[40:41], 1, v3
	s_cbranch_vccnz .LBB0_770
	s_setprio 1
	s_waitcnt vmcnt(4)
	s_barrier

; __device__ __forceinline__ s16x4 vtr(const ALDS unsigned char* p) { return __builtin_bit_cast(s16x4, __builtin_amdgcn_ds_read_tr16_b64_v4i16((ALDS s16x4*)p)); }
; template <int DV, bool BAND> ...
;     ...
;         float ssum = 0.f;
;         bf16x8 pfs[4];
;     ...
;         ATT_EXP_SLICE(p0, 0, pfs[0]);
; #pragma unroll
;         for (int ks = 0; ks < 4; ++ks) {
;             if (ks + 1 < 4) {
; #pragma unroll
;                 for (int db = 0; db < NDB; ++db) { vlo[(ks + 1) & 1][db] = vtr(sb + va[db] + (ks + 1) * (16 * ROWB)); vhh[(ks + 1) & 1][db] = vtr(sb + va[db] + (ks + 1) * (16 * ROWB) + 4 * ROWB); }
;             }
; #pragma unroll
;             for (int db = 0; db < NDB; ++db) {
;                 const s16x4 lo = vlo[ks & 1][db], hh = vhh[ks & 1][db];
;                 const bf16x8 vf = (bf16x8){lo[0], lo[1], lo[2], lo[3], hh[0], hh[1], hh[2], hh[3]};
;                 o[db] = __builtin_amdgcn_mfma_f32_32x32x16_bf16(vf, pfs[ks], o[db], 0, 0, 0);
;             }
;             if (ks == 0) ATT_EXP_SLICE(p0, 8, pfs[1]);
;             if (ks == 1) ATT_EXP_SLICE(p1, 0, pfs[2]);
;             if (ks == 2) ATT_EXP_SLICE(p1, 8, pfs[3]);
;         }
;     ...
;         l += ssum;
;         s_cur = (s_cur == 2 * SLOT) ? 0 : s_cur + SLOT; s_n2 = (s_n2 == 2 * SLOT) ? 0 : s_n2 + SLOT;
.LBB0_773:
	v_exp_f32_e32 v101, v84
	v_exp_f32_e32 v103, v85
	v_exp_f32_e32 v85, v86
	v_exp_f32_e32 v87, v87
	v_exp_f32_e32 v100, v88
	v_exp_f32_e32 v102, v89
	v_exp_f32_e32 v84, v90
	v_exp_f32_e32 v86, v91
	v_cvt_pk_bf16_f32 v88, v101, v103
	v_cvt_pk_bf16_f32 v89, v85, v87
	v_cvt_pk_bf16_f32 v90, v100, v102
	v_cvt_pk_bf16_f32 v91, v84, v86
	ds_read_b64_tr_b16 v[110:111], v108 offset:20480
	ds_read_b64_tr_b16 v[112:113], v108 offset:21504
	ds_read_b64_tr_b16 v[130:131], v107 offset:4096
	ds_read_b64_tr_b16 v[132:133], v107 offset:5120
	ds_read_b64_tr_b16 v[134:135], v106 offset:4096
	ds_read_b64_tr_b16 v[136:137], v106 offset:5120
	ds_read_b64_tr_b16 v[138:139], v67 offset:4096
	ds_read_b64_tr_b16 v[140:141], v67 offset:5120
	s_waitcnt vmcnt(4)
	s_barrier
	s_waitcnt lgkmcnt(14)
	v_mfma_f32_32x32x16_bf16 v[50:65], v[14:17], v[88:91], 0
	v_exp_f32_e32 v105, v92
	v_exp_f32_e32 v93, v93
	v_exp_f32_e32 v104, v94
	v_exp_f32_e32 v92, v95
	ds_read_b64_tr_b16 v[142:143], v108 offset:24576
	ds_read_b64_tr_b16 v[144:145], v108 offset:25600
	ds_read_b64_tr_b16 v[160:161], v107 offset:8192
	ds_read_b64_tr_b16 v[162:163], v107 offset:9216
	ds_read_b64_tr_b16 v[164:165], v106 offset:8192
	ds_read_b64_tr_b16 v[166:167], v106 offset:9216
	ds_read_b64_tr_b16 v[168:169], v67 offset:8192
	ds_read_b64_tr_b16 v[170:171], v67 offset:9216
	v_cvt_pk_bf16_f32 v94, v105, v93
	v_exp_f32_e32 v0, v76
	s_waitcnt lgkmcnt(14)
	v_mfma_f32_32x32x16_bf16 v[34:49], v[10:13], v[88:91], 0
	v_cvt_pk_bf16_f32 v95, v104, v92
	v_exp_f32_e32 v76, v77
	v_exp_f32_e32 v78, v78
	v_exp_f32_e32 v80, v80
	v_exp_f32_e32 v82, v82
	s_mov_b32 s4, 1
	s_mov_b32 s5, 0x18000
	v_mfma_f32_32x32x16_bf16 v[18:33], v[2:5], v[88:91], 0
	s_mov_b32 s6, 0x8000
	s_movk_i32 s49, 0x900
	v_mfma_f32_32x32x16_bf16 v[2:17], v[6:9], v[88:91], 0
	v_exp_f32_e32 v89, v96
	v_exp_f32_e32 v91, v97
	v_exp_f32_e32 v88, v98
	v_exp_f32_e32 v90, v99
	v_exp_f32_e32 v99, v68
	v_cvt_pk_bf16_f32 v96, v89, v91
	v_exp_f32_e32 v98, v79
	v_cvt_pk_bf16_f32 v97, v88, v90
	s_nop 1
	v_mfma_f32_32x32x16_bf16 v[50:65], v[110:113], v[94:97], v[50:65]
	v_exp_f32_e32 v113, v69
	v_exp_f32_e32 v112, v83
	v_cvt_pk_bf16_f32 v68, v99, v113
	s_waitcnt lgkmcnt(12)
	v_mfma_f32_32x32x16_bf16 v[34:49], v[130:133], v[94:97], v[34:49]
	s_waitcnt lgkmcnt(10)
	v_mfma_f32_32x32x16_bf16 v[18:33], v[134:137], v[94:97], v[18:33]
	v_exp_f32_e32 v134, v70
	v_exp_f32_e32 v135, v71
	v_exp_f32_e32 v136, v72
	v_exp_f32_e32 v137, v73
	v_cvt_pk_bf16_f32 v69, v134, v135
	v_cvt_pk_bf16_f32 v70, v136, v137
	s_waitcnt lgkmcnt(8)
	v_mfma_f32_32x32x16_bf16 v[2:17], v[138:141], v[94:97], v[2:17]
	v_exp_f32_e32 v138, v74
	v_exp_f32_e32 v139, v75
	ds_read_b64_tr_b16 v[72:73], v108 offset:28672
	ds_read_b64_tr_b16 v[74:75], v108 offset:29696
	ds_read_b64_tr_b16 v[94:95], v107 offset:12288
	ds_read_b64_tr_b16 v[96:97], v107 offset:13312
	ds_read_b64_tr_b16 v[108:109], v106 offset:12288
	ds_read_b64_tr_b16 v[110:111], v106 offset:13312
	ds_read_b64_tr_b16 v[130:131], v67 offset:12288
	ds_read_b64_tr_b16 v[132:133], v67 offset:13312
	v_exp_f32_e32 v106, v81
	v_add_f32_e32 v81, v113, v99
	v_cvt_pk_bf16_f32 v71, v138, v139
	v_add_f32_e32 v107, v135, v134
	v_add_f32_e32 v83, v137, v136
	s_waitcnt lgkmcnt(14)
	v_mfma_f32_32x32x16_bf16 v[50:65], v[142:145], v[68:71], v[50:65]
	v_add_f32_e32 v113, v139, v138
	v_mov_b32_e32 v67, v66
	s_waitcnt lgkmcnt(12)
	v_mfma_f32_32x32x16_bf16 v[34:49], v[160:163], v[68:71], v[34:49]
	s_waitcnt lgkmcnt(10)
	v_mfma_f32_32x32x16_bf16 v[18:33], v[164:167], v[68:71], v[18:33]
	s_waitcnt lgkmcnt(8)
	v_mfma_f32_32x32x16_bf16 v[2:17], v[168:171], v[68:71], v[2:17]
	v_cvt_pk_bf16_f32 v68, v0, v76
	v_cvt_pk_bf16_f32 v69, v78, v98
	v_cvt_pk_bf16_f32 v70, v80, v106
	v_cvt_pk_bf16_f32 v71, v82, v112
	s_waitcnt lgkmcnt(6)
	s_nop 0
	v_mfma_f32_32x32x16_bf16 v[50:65], v[72:75], v[68:71], v[50:65]
	v_add_f32_e64 v72, v102, v100
	v_add_f32_e64 v73, v103, v101
	v_add_f32_e64 v74, v86, v84
	v_add_f32_e64 v75, v87, v85
	v_add_f32_e64 v72, v74, v72
	v_add_f32_e64 v73, v75, v73
	v_pk_add_f32 v[74:75], v[106:107], v[80:81]
	v_pk_add_f32 v[72:73], v[72:73], v[72:73] op_sel_hi:[0,1]
	v_mov_b32_e32 v77, v73
	s_waitcnt lgkmcnt(4)
	v_mfma_f32_32x32x16_bf16 v[34:49], v[94:97], v[68:71], v[34:49]
	v_add_f32_e64 v80, v112, v82
	v_add_f32_e64 v81, v113, v83
	v_mov_b32_e32 v72, v66
	v_add_f32_e64 v74, v80, v74
	v_add_f32_e64 v75, v81, v75
	v_mov_b32_e32 v73, v66
	v_mov_b32_e32 v80, v66
	v_mov_b32_e32 v81, v66
	s_waitcnt lgkmcnt(2)
	v_mfma_f32_32x32x16_bf16 v[18:33], v[108:111], v[68:71], v[18:33]
	s_waitcnt lgkmcnt(0)
	v_mfma_f32_32x32x16_bf16 v[2:17], v[130:133], v[68:71], v[2:17]
	v_add_f32_e64 v68, v92, v104
	v_add_f32_e64 v69, v93, v105
	v_add_f32_e64 v70, v90, v88
	v_add_f32_e64 v71, v91, v89
	v_pk_add_f32 v[68:69], v[68:69], v[68:69] op_sel_hi:[0,1]
	v_pk_add_f32 v[70:71], v[70:71], v[70:71] op_sel_hi:[0,1]
	v_mov_b32_e32 v99, v71
	v_mov_b32_e32 v79, v69
	v_pk_add_f32 v[68:69], v[98:99], v[78:79]
	v_pk_add_f32 v[70:71], v[76:77], v[0:1]
	v_mov_b32_e32 v76, v66
	v_pk_add_f32 v[68:69], v[68:69], v[70:71]
	v_mov_b32_e32 v70, v66
	v_pk_add_f32 v[68:69], v[74:75], v[68:69]
	v_mov_b32_e32 v71, v66
	v_add_f32_e32 v160, v68, v69
	v_mov_b32_e32 v68, v66
	v_mov_b32_e32 v69, v66
	v_mov_b32_e32 v74, v66
	v_mov_b32_e32 v75, v66
	v_mov_b32_e32 v77, v66
	v_mov_b32_e32 v78, v66
	v_mov_b32_e32 v79, v66
	s_branch .LBB0_775
; __device__ __forceinline__ s16x4 vtr(const ALDS unsigned char* p) { return __builtin_bit_cast(s16x4, __builtin_amdgcn_ds_read_tr16_b64_v4i16((ALDS s16x4*)p)); }
; template <int DV, bool BAND> ...
;     ...
;         float ssum = 0.f;
;         bf16x8 pfs[4];
;     ...
;         ATT_EXP_SLICE(p0, 0, pfs[0]);
; #pragma unroll
;         for (int ks = 0; ks < 4; ++ks) {
;             if (ks + 1 < 4) {
; #pragma unroll
;                 for (int db = 0; db < NDB; ++db) { vlo[(ks + 1) & 1][db] = vtr(sb + va[db] + (ks + 1) * (16 * ROWB)); vhh[(ks + 1) & 1][db] = vtr(sb + va[db] + (ks + 1) * (16 * ROWB) + 4 * ROWB); }
;             }
; #pragma unroll
;             for (int db = 0; db < NDB; ++db) {
;                 const s16x4 lo = vlo[ks & 1][db], hh = vhh[ks & 1][db];
;                 const bf16x8 vf = (bf16x8){lo[0], lo[1], lo[2], lo[3], hh[0], hh[1], hh[2], hh[3]};
;                 o[db] = __builtin_amdgcn_mfma_f32_32x32x16_bf16(vf, pfs[ks], o[db], 0, 0, 0);
;             }
;             if (ks == 0) ATT_EXP_SLICE(p0, 8, pfs[1]);
;             if (ks == 1) ATT_EXP_SLICE(p1, 0, pfs[2]);
;             if (ks == 2) ATT_EXP_SLICE(p1, 8, pfs[3]);
;         }
;     ...
;         l += ssum;
;         s_cur = (s_cur == 2 * SLOT) ? 0 : s_cur + SLOT; s_n2 = (s_n2 == 2 * SLOT) ? 0 : s_n2 + SLOT;
.LBB0_774:
	v_exp_f32_e32 v167, v98
	v_exp_f32_e32 v169, v99
	v_exp_f32_e32 v171, v100
	v_exp_f32_e32 v173, v101
	v_exp_f32_e32 v166, v102
	v_exp_f32_e32 v168, v103
	v_exp_f32_e32 v170, v104
	v_exp_f32_e32 v172, v105
	v_cvt_pk_bf16_f32 v98, v167, v169
	v_cvt_pk_bf16_f32 v99, v171, v173
	v_cvt_pk_bf16_f32 v100, v166, v168
	v_cvt_pk_bf16_f32 v101, v170, v172
	ds_read_b64_tr_b16 v[102:103], v164 offset:20480
	ds_read_b64_tr_b16 v[104:105], v164 offset:21504
	s_waitcnt vmcnt(4)
	s_barrier
	s_waitcnt lgkmcnt(8)
	v_mfma_f32_32x32x16_bf16 v[50:65], v[142:145], v[98:101], v[50:65]
	v_exp_f32_e32 v142, v82
	v_exp_f32_e32 v143, v83
	v_exp_f32_e32 v144, v84
	v_exp_f32_e32 v145, v85
	v_exp_f32_e32 v165, v86
	v_exp_f32_e32 v174, v87
	v_exp_f32_e32 v175, v88
	s_waitcnt lgkmcnt(6)
	v_mfma_f32_32x32x16_bf16 v[34:49], v[138:141], v[98:101], v[34:49]
	v_exp_f32_e32 v139, v110
	v_exp_f32_e32 v141, v111
	v_exp_f32_e32 v138, v112
	v_exp_f32_e32 v140, v113
	v_exp_f32_e32 v176, v89
	v_cvt_pk_bf16_f32 v86, v142, v143
	v_cvt_pk_bf16_f32 v87, v144, v145
	s_waitcnt lgkmcnt(4)
	v_mfma_f32_32x32x16_bf16 v[18:33], v[134:137], v[98:101], v[18:33]
	v_exp_f32_e32 v135, v106
	v_exp_f32_e32 v137, v107
	v_exp_f32_e32 v134, v108
	v_exp_f32_e32 v136, v109
	ds_read_b64_tr_b16 v[106:107], v164 offset:24576
	ds_read_b64_tr_b16 v[108:109], v164 offset:25600
	v_cvt_pk_bf16_f32 v88, v165, v174
	v_cvt_pk_bf16_f32 v89, v175, v176
	s_waitcnt lgkmcnt(4)
	v_mfma_f32_32x32x16_bf16 v[2:17], v[130:133], v[98:101], v[2:17]
	v_cvt_pk_bf16_f32 v98, v135, v137
	v_cvt_pk_bf16_f32 v99, v134, v136
	v_cvt_pk_bf16_f32 v100, v139, v141
	v_cvt_pk_bf16_f32 v101, v138, v140
	v_add_f32_e64 v82, v168, v166
	v_add_f32_e64 v83, v169, v167
	v_exp_f32_e32 v0, v90
	v_exp_f32_e32 v90, v94
	s_waitcnt lgkmcnt(2)
	v_mfma_f32_32x32x16_bf16 v[50:65], v[102:105], v[98:101], v[50:65]
	ds_read_b64_tr_b16 v[102:103], v163 offset:4096
	ds_read_b64_tr_b16 v[104:105], v163 offset:5120
	ds_read_b64_tr_b16 v[110:111], v164 offset:29696
	v_exp_f32_e32 v94, v96
	v_exp_f32_e32 v96, v97
	v_add_f32_e32 v97, v176, v175
	s_add_i32 s7, s6, 0x8000
	s_cmp_lg_u32 s6, 0x18000
	s_cselect_b32 s6, s7, 0
	s_waitcnt lgkmcnt(1)
	v_mfma_f32_32x32x16_bf16 v[34:49], v[102:105], v[98:101], v[34:49]
	ds_read_b64_tr_b16 v[102:103], v161 offset:4096
	ds_read_b64_tr_b16 v[104:105], v161 offset:5120
	ds_read_b64_tr_b16 v[130:131], v161 offset:8192
	ds_read_b64_tr_b16 v[132:133], v161 offset:9216
	s_add_i32 s7, s5, 0x8000
	s_cmp_lg_u32 s5, 0x18000
	s_cselect_b32 s5, s7, 0
	s_add_i32 s4, s4, 1
	s_cmp_lg_u32 s4, 64
	s_waitcnt lgkmcnt(2)
	v_mfma_f32_32x32x16_bf16 v[18:33], v[102:105], v[98:101], v[18:33]
	ds_read_b64_tr_b16 v[102:103], v162 offset:4096
	ds_read_b64_tr_b16 v[104:105], v162 offset:5120
	ds_read_b64_tr_b16 v[84:85], v161 offset:13312
	s_waitcnt lgkmcnt(1)
	v_mfma_f32_32x32x16_bf16 v[2:17], v[102:105], v[98:101], v[2:17]
	v_add_f32_e64 v102, v172, v170
	v_add_f32_e64 v103, v173, v171
	v_add_f32_e64 v82, v102, v82
	v_add_f32_e64 v83, v103, v83
	v_mfma_f32_32x32x16_bf16 v[50:65], v[106:109], v[86:89], v[50:65]
	ds_read_b64_tr_b16 v[98:99], v163 offset:8192
	ds_read_b64_tr_b16 v[100:101], v163 offset:9216
	ds_read_b64_tr_b16 v[108:109], v164 offset:28672
	ds_read_b64_tr_b16 v[102:103], v163 offset:12288
	ds_read_b64_tr_b16 v[104:105], v163 offset:13312
	v_pk_add_f32 v[106:107], v[82:83], v[82:83] op_sel_hi:[0,1]
	v_pk_add_f32 v[82:83], v[136:137], v[134:135]
	v_exp_f32_e32 v106, v91
	v_pk_add_f32 v[112:113], v[82:83], v[82:83] op_sel_hi:[0,1]
	v_pk_add_f32 v[82:83], v[140:141], v[138:139]
	s_waitcnt lgkmcnt(3)
	v_mfma_f32_32x32x16_bf16 v[34:49], v[98:101], v[86:89], v[34:49]
	ds_read_b64_tr_b16 v[98:99], v162 offset:8192
	ds_read_b64_tr_b16 v[100:101], v162 offset:9216
	v_add_f32_e64 v134, v82, v82
	v_add_f32_e64 v135, v82, v83
	v_exp_f32_e32 v112, v92
	v_exp_f32_e32 v134, v93
	v_exp_f32_e32 v92, v95
	v_add_f32_e32 v91, v143, v142
	v_add_f32_e32 v93, v145, v144
	v_mfma_f32_32x32x16_bf16 v[18:33], v[130:133], v[86:89], v[18:33]
	ds_read_b64_tr_b16 v[130:131], v162 offset:12288
	ds_read_b64_tr_b16 v[132:133], v162 offset:13312
	ds_read_b64_tr_b16 v[82:83], v161 offset:12288
	v_add_f32_e32 v95, v174, v165
	s_waitcnt lgkmcnt(3)
	v_mfma_f32_32x32x16_bf16 v[2:17], v[98:101], v[86:89], v[2:17]
	v_cvt_pk_bf16_f32 v86, v0, v106
	v_cvt_pk_bf16_f32 v87, v112, v134
	v_cvt_pk_bf16_f32 v88, v90, v92
	v_cvt_pk_bf16_f32 v89, v94, v96
	v_add_f32_e64 v98, v106, v0
	v_add_f32_e64 v99, v107, v1
	v_pk_add_f32 v[100:101], v[134:135], v[112:113]
	v_pk_add_f32 v[90:91], v[92:93], v[90:91]
	v_mfma_f32_32x32x16_bf16 v[50:65], v[108:111], v[86:89], v[50:65]
	v_add_f32_e64 v92, v96, v94
	v_add_f32_e64 v93, v97, v95
	v_add_f32_e64 v98, v100, v98
	v_add_f32_e64 v99, v101, v99
	v_add_f32_e64 v90, v92, v90
	v_add_f32_e64 v91, v93, v91
	v_pk_add_f32 v[90:91], v[90:91], v[98:99]
	s_nop 0
	v_add_f32_e32 v0, v90, v91
	v_mfma_f32_32x32x16_bf16 v[34:49], v[102:105], v[86:89], v[34:49]
	v_add_f32_e32 v160, v160, v0
	s_waitcnt lgkmcnt(0)
	v_mfma_f32_32x32x16_bf16 v[18:33], v[82:85], v[86:89], v[18:33]
	v_mfma_f32_32x32x16_bf16 v[2:17], v[130:133], v[86:89], v[2:17]
	s_cbranch_scc0 .LBB0_777

; template <int DV, bool BAND> ...
;     ...
;     }
;     __builtin_amdgcn_s_setprio(0);
;     asm volatile("s_waitcnt vmcnt(0) lgkmcnt(0)\n\ts_barrier" ::: "memory");
.LBB0_777:
	v_readlane_b32 s4, v254, 33
	v_readlane_b32 s5, v254, 34
	s_and_b64 vcc, exec, s[4:5]
	s_cbranch_vccnz .Ldiff_stag_out
	s_barrier
